# S36: S35 + ctx-unit attention epilogue gets the same treatment as the latent one (80 ds_bpermute -> DPP/permlane16, next-row X-exchange reads prefetched, subln_w loads issued together)
# speedup vs baseline: 1.0039x; 1.0039x over previous
; __device__ __forceinline__ unsigned f2bf(float f) { unsigned u = __builtin_bit_cast(unsigned, f); return (u + 0x7fffu + ((u >> 16) & 1u)) >> 16; }
; __device__ __forceinline__ int crow(int r, int hi) { return (r & 3) + 8 * (r >> 2) + 4 * hi; }
; __device__ __forceinline__ void attn_unit(const bf16* __restrict__ Qb, const bf16* __restrict__ Kh, const bf16* __restrict__ Vh, int klat0, int nlt, int kctx0, int NT,
;                                           float lam, float post, const float* __restrict__ subw, bf16* __restrict__ Ob, char* lds) {
;     ...
;     float sw[4];
; #pragma unroll
;     for (int d0 = 0; d0 < 4; ++d0) sw[d0] = subw[d0 * 32 + r32_e] * post;
;     bf16* Ow = Ob + (long)(wq_e * 32) * DM;
; #pragma unroll
;     for (int r = 0; r < 16; ++r) { const int orow = crow(r, hi_e); float v[4]; float ss = 0.f;
; #pragma unroll
;       for (int d0 = 0; d0 < 4; ++d0) { v[d0] = o[d0][r] - lam * X[(wq_e * 32 + orow) * 128 + d0 * 32 + r32_e]; ss += v[d0] * v[d0]; }
;       ss += __shfl_xor(ss, 1); ss += __shfl_xor(ss, 2); ss += __shfl_xor(ss, 4); ss += __shfl_xor(ss, 8); ss += __shfl_xor(ss, 16);
;       const float rs = 1.0f / sqrtf(ss * (1.0f / 128.0f) + LN_EPS);
; #pragma unroll
;       for (int d0 = 0; d0 < 4; ++d0) Ow[(long)orow * DM + d0 * 32 + r32_e] = (bf16)f2bf(v[d0] * rs * sw[d0]); }
.LBB0_745:
	s_andn2_b64 vcc, exec, s[4:5]
	s_waitcnt lgkmcnt(0)
	s_barrier
	s_cbranch_vccnz .LBB0_747
	v_lshlrev_b32_e32 v30, 2, v125
	v_ashrrev_i32_e32 v125, 31, v124
	v_lshl_add_u64 v[4:5], v[124:125], 2, s[2:3]
	global_load_dword v8, v[4:5], off
	global_load_dword v244, v[4:5], off offset:128
	global_load_dword v245, v[4:5], off offset:256
	global_load_dword v246, v[4:5], off offset:384
	s_lshl_b64 s[0:1], s[58:59], 12
	v_readlane_b32 s4, v251, 21
	s_add_u32 s0, s4, s0
	v_readlane_b32 s4, v251, 22
	s_addc_u32 s1, s4, s1
	s_mov_b32 s4, 0xf800000
	s_add_u32 s0, s0, s9
	s_addc_u32 s1, s1, 0
	v_ashrrev_i32_e32 v31, 31, v30
	v_add_u32_e32 v28, 8, v30
	v_add_u32_e32 v26, 9, v30
	v_add_u32_e32 v24, 10, v30
	v_add_u32_e32 v22, 11, v30
	v_add_u32_e32 v20, 16, v30
	v_add_u32_e32 v18, 17, v30
	v_add_u32_e32 v16, 18, v30
	v_add_u32_e32 v14, 19, v30
	v_add_u32_e32 v12, 24, v30
	v_add_u32_e32 v10, 25, v30
	v_add_u32_e32 v6, 26, v30
	v_add_u32_e32 v2, 27, v30
	v_ashrrev_i32_e32 v29, 31, v28
	v_ashrrev_i32_e32 v27, 31, v26
	v_ashrrev_i32_e32 v25, 31, v24
	v_ashrrev_i32_e32 v23, 31, v22
	v_ashrrev_i32_e32 v21, 31, v20
	v_ashrrev_i32_e32 v19, 31, v18
	v_ashrrev_i32_e32 v17, 31, v16
	v_ashrrev_i32_e32 v15, 31, v14
	v_ashrrev_i32_e32 v13, 31, v12
	v_ashrrev_i32_e32 v11, 31, v10
	v_ashrrev_i32_e32 v7, 31, v6
	v_ashrrev_i32_e32 v3, 31, v2
	s_waitcnt vmcnt(0)
	v_mul_f32_e32 v34, v161, v8
	v_mul_f32_e32 v35, v161, v244
	v_mul_f32_e32 v36, v161, v245
	v_lshlrev_b32_e32 v8, 5, v100
	v_ashrrev_i32_e32 v9, 31, v8
	v_mul_f32_e32 v37, v161, v246
	v_lshlrev_b64 v[4:5], 12, v[8:9]
	v_add_u32_e32 v9, v30, v8
	v_lshl_add_u32 v9, v9, 7, v124
	v_lshl_add_u32 v9, v9, 2, 0
	ds_read2_b32 v[54:55], v9 offset1:32
	v_lshl_add_u64 v[4:5], s[0:1], 0, v[4:5]
	v_lshl_add_u64 v[4:5], v[124:125], 1, v[4:5]
	s_waitcnt lgkmcnt(0)
	v_fma_f32 v56, -v160, v54, v121
	v_fma_f32 v57, -v160, v55, v122
	ds_read2_b32 v[54:55], v9 offset0:64 offset1:96
	v_mul_f32_e32 v58, v57, v57
	v_fmac_f32_e32 v58, v56, v56
	s_waitcnt lgkmcnt(0)
	v_or_b32_e32 v245, 1, v30
	v_add_u32_e32 v244, v245, v8
	v_lshl_add_u32 v244, v244, 7, v124
	v_lshl_add_u32 v244, v244, 2, 0
	ds_read2_b32 v[240:241], v244 offset1:32
	ds_read2_b32 v[242:243], v244 offset0:64 offset1:96
	v_fma_f32 v9, -v160, v54, v119
	v_fmac_f32_e32 v58, v9, v9
	v_fma_f32 v59, -v160, v55, v120
	v_fmac_f32_e32 v58, v59, v59
	s_nop 1
	v_mov_b32_dpp v54, v58 quad_perm:[1,0,3,2] row_mask:0xf bank_mask:0xf
	v_add_f32_e32 v54, v58, v54
	s_nop 1
	v_mov_b32_dpp v55, v54 quad_perm:[2,3,0,1] row_mask:0xf bank_mask:0xf
	v_add_f32_e32 v54, v54, v55
	s_nop 1
	v_mov_b32_dpp v55, v54 row_half_mirror row_mask:0xf bank_mask:0xf
	s_nop 1
	v_mov_b32_dpp v55, v55 quad_perm:[3,2,1,0] row_mask:0xf bank_mask:0xf
	v_add_f32_e32 v54, v54, v55
	s_nop 1
	v_mov_b32_dpp v55, v54 row_ror:8 row_mask:0xf bank_mask:0xf
	v_add_f32_e32 v54, v54, v55
	v_mov_b32_e32 v55, v54
	s_nop 1
	v_permlane16_swap_b32_e32 v54, v55
	v_add_f32_e32 v54, v54, v55
	v_fmamk_f32 v54, v54, 0x3c000000, v179
	v_cmp_gt_f32_e32 vcc, s4, v54
	v_mul_f32_e32 v55, 0x4f800000, v54
	s_nop 0
	v_cndmask_b32_e32 v54, v54, v55, vcc
	v_sqrt_f32_e32 v55, v54
	s_nop 0
	v_add_u32_e32 v58, -1, v55
	v_fma_f32 v60, -v58, v55, v54
	v_cmp_ge_f32_e64 s[0:1], 0, v60
	v_add_u32_e32 v60, 1, v55
	s_nop 0
	v_cndmask_b32_e64 v58, v55, v58, s[0:1]
	v_fma_f32 v55, -v60, v55, v54
	v_cmp_lt_f32_e64 s[0:1], 0, v55
	s_nop 1
	v_cndmask_b32_e64 v55, v58, v60, s[0:1]
	v_mul_f32_e32 v58, 0x37800000, v55
	v_cndmask_b32_e32 v55, v55, v58, vcc
	v_cmp_class_f32_e32 vcc, v54, v180
	s_nop 1
	v_cndmask_b32_e32 v54, v55, v54, vcc
	v_div_scale_f32 v55, s[0:1], v54, v54, 1.0
	v_rcp_f32_e32 v58, v55
	s_nop 0
	v_fma_f32 v60, -v55, v58, 1.0
	v_fmac_f32_e32 v58, v60, v58
	v_div_scale_f32 v60, vcc, 1.0, v54, 1.0
	v_mul_f32_e32 v61, v60, v58
	v_fma_f32 v62, -v55, v61, v60
	v_fmac_f32_e32 v61, v62, v58
	v_fma_f32 v55, -v55, v61, v60
	v_div_fmas_f32 v55, v55, v58, v61
	v_div_fixup_f32 v58, v55, v54, 1.0
	v_lshlrev_b64 v[54:55], 12, v[30:31]
	v_mul_f32_e32 v31, v56, v58
	v_mul_f32_e32 v31, v34, v31
	v_bfe_u32 v56, v31, 16, 1
	v_lshl_add_u64 v[54:55], v[4:5], 0, v[54:55]
	v_add3_u32 v31, v31, v56, s70
	global_store_short_d16_hi v[54:55], v31, off
	v_mul_f32_e32 v31, v57, v58
	v_mul_f32_e32 v31, v35, v31
	v_bfe_u32 v56, v31, 16, 1
	v_mul_f32_e32 v9, v9, v58
	v_add3_u32 v31, v31, v56, s70
	v_mul_f32_e32 v9, v36, v9
	global_store_short_d16_hi v[54:55], v31, off offset:64
	v_bfe_u32 v31, v9, 16, 1
	v_add3_u32 v9, v9, v31, s70
	global_store_short_d16_hi v[54:55], v9, off offset:128
	v_mul_f32_e32 v9, v59, v58
	v_mul_f32_e32 v9, v37, v9
	v_bfe_u32 v31, v9, 16, 1
	v_add3_u32 v9, v9, v31, s70
	global_store_short_d16_hi v[54:55], v9, off offset:192
	v_or_b32_e32 v54, 1, v30
	v_add_u32_e32 v9, v54, v8
	v_lshl_add_u32 v9, v9, 7, v124
	v_lshl_add_u32 v9, v9, 2, 0
	s_waitcnt lgkmcnt(1)
	v_fma_f32 v31, -v160, v240, v107
	v_fma_f32 v58, -v160, v241, v108
	v_mul_f32_e32 v55, v58, v58
	v_fmac_f32_e32 v55, v31, v31
	s_waitcnt lgkmcnt(0)
; __device__ __forceinline__ unsigned f2bf(float f) { unsigned u = __builtin_bit_cast(unsigned, f); return (u + 0x7fffu + ((u >> 16) & 1u)) >> 16; }
; __device__ __forceinline__ int crow(int r, int hi) { return (r & 3) + 8 * (r >> 2) + 4 * hi; }
; __device__ __forceinline__ void attn_unit(const bf16* __restrict__ Qb, const bf16* __restrict__ Kh, const bf16* __restrict__ Vh, int klat0, int nlt, int kctx0, int NT,
;                                           float lam, float post, const float* __restrict__ subw, bf16* __restrict__ Ob, char* lds) {
;     ...
;     for (int r = 0; r < 16; ++r) { const int orow = crow(r, hi_e); float v[4]; float ss = 0.f;
; #pragma unroll
;       for (int d0 = 0; d0 < 4; ++d0) { v[d0] = o[d0][r] - lam * X[(wq_e * 32 + orow) * 128 + d0 * 32 + r32_e]; ss += v[d0] * v[d0]; }
;       ss += __shfl_xor(ss, 1); ss += __shfl_xor(ss, 2); ss += __shfl_xor(ss, 4); ss += __shfl_xor(ss, 8); ss += __shfl_xor(ss, 16);
;       const float rs = 1.0f / sqrtf(ss * (1.0f / 128.0f) + LN_EPS);
; #pragma unroll
;       for (int d0 = 0; d0 < 4; ++d0) Ow[(long)orow * DM + d0 * 32 + r32_e] = (bf16)f2bf(v[d0] * rs * sw[d0]); }
	v_or_b32_e32 v245, 2, v30
	v_add_u32_e32 v244, v245, v8
	v_lshl_add_u32 v244, v244, 7, v124
	v_lshl_add_u32 v244, v244, 2, 0
	ds_read2_b32 v[236:237], v244 offset1:32
	ds_read2_b32 v[238:239], v244 offset0:64 offset1:96
	v_fma_f32 v9, -v160, v242, v105
	v_fmac_f32_e32 v55, v9, v9
	v_fma_f32 v56, -v160, v243, v106
	v_fmac_f32_e32 v55, v56, v56
	s_nop 1
	v_mov_b32_dpp v57, v55 quad_perm:[1,0,3,2] row_mask:0xf bank_mask:0xf
	v_add_f32_e32 v55, v55, v57
	s_nop 1
	v_mov_b32_dpp v57, v55 quad_perm:[2,3,0,1] row_mask:0xf bank_mask:0xf
	v_add_f32_e32 v55, v55, v57
	s_nop 1
	v_mov_b32_dpp v57, v55 row_half_mirror row_mask:0xf bank_mask:0xf
	s_nop 1
	v_mov_b32_dpp v57, v57 quad_perm:[3,2,1,0] row_mask:0xf bank_mask:0xf
	v_add_f32_e32 v55, v55, v57
	s_nop 1
	v_mov_b32_dpp v57, v55 row_ror:8 row_mask:0xf bank_mask:0xf
	v_add_f32_e32 v55, v55, v57
	v_mov_b32_e32 v57, v55
	s_nop 1
	v_permlane16_swap_b32_e32 v55, v57
	v_add_f32_e32 v55, v55, v57
	v_fmamk_f32 v55, v55, 0x3c000000, v179
	v_cmp_gt_f32_e32 vcc, s4, v55
	v_mul_f32_e32 v57, 0x4f800000, v55
	s_nop 0
	v_cndmask_b32_e32 v55, v55, v57, vcc
	v_sqrt_f32_e32 v57, v55
	s_nop 0
	v_add_u32_e32 v59, -1, v57
	v_fma_f32 v60, -v59, v57, v55
	v_cmp_ge_f32_e64 s[0:1], 0, v60
	v_add_u32_e32 v60, 1, v57
	s_nop 0
	v_cndmask_b32_e64 v59, v57, v59, s[0:1]
	v_fma_f32 v57, -v60, v57, v55
	v_cmp_lt_f32_e64 s[0:1], 0, v57
	s_nop 1
	v_cndmask_b32_e64 v57, v59, v60, s[0:1]
	v_mul_f32_e32 v59, 0x37800000, v57
	v_cndmask_b32_e32 v57, v57, v59, vcc
	v_cmp_class_f32_e32 vcc, v55, v180
	s_nop 1
	v_cndmask_b32_e32 v55, v57, v55, vcc
	v_div_scale_f32 v57, s[0:1], v55, v55, 1.0
	v_rcp_f32_e32 v59, v57
	s_nop 0
	v_fma_f32 v60, -v57, v59, 1.0
	v_fmac_f32_e32 v59, v60, v59
	v_div_scale_f32 v60, vcc, 1.0, v55, 1.0
	v_mul_f32_e32 v61, v60, v59
	v_fma_f32 v62, -v57, v61, v60
	v_fmac_f32_e32 v61, v62, v59
	v_fma_f32 v57, -v57, v61, v60
	v_div_fmas_f32 v57, v57, v59, v61
	v_div_fixup_f32 v57, v57, v55, 1.0
	v_mul_f32_e32 v31, v31, v57
	v_ashrrev_i32_e32 v55, 31, v54
	v_mul_f32_e32 v31, v34, v31
	v_lshlrev_b64 v[54:55], 12, v[54:55]
	v_bfe_u32 v59, v31, 16, 1
	v_lshl_add_u64 v[54:55], v[4:5], 0, v[54:55]
	v_add3_u32 v31, v31, v59, s70
	global_store_short_d16_hi v[54:55], v31, off
	v_mul_f32_e32 v31, v58, v57
	v_mul_f32_e32 v31, v35, v31
	v_bfe_u32 v58, v31, 16, 1
	v_mul_f32_e32 v9, v9, v57
	v_add3_u32 v31, v31, v58, s70
	v_mul_f32_e32 v9, v36, v9
	global_store_short_d16_hi v[54:55], v31, off offset:64
	v_bfe_u32 v31, v9, 16, 1
	v_add3_u32 v9, v9, v31, s70
	global_store_short_d16_hi v[54:55], v9, off offset:128
	v_mul_f32_e32 v9, v56, v57
	v_mul_f32_e32 v9, v37, v9
	v_bfe_u32 v31, v9, 16, 1
	v_add3_u32 v9, v9, v31, s70
	global_store_short_d16_hi v[54:55], v9, off offset:192
	v_or_b32_e32 v54, 2, v30
	v_add_u32_e32 v9, v54, v8
	v_lshl_add_u32 v9, v9, 7, v124
	v_lshl_add_u32 v9, v9, 2, 0
	v_or_b32_e32 v30, 3, v30
	s_waitcnt lgkmcnt(1)
	v_fma_f32 v31, -v160, v236, v103
	v_fma_f32 v58, -v160, v237, v104
	v_mul_f32_e32 v55, v58, v58
	v_fmac_f32_e32 v55, v31, v31
	s_waitcnt lgkmcnt(0)
	v_add_u32_e32 v244, v30, v8
	v_lshl_add_u32 v244, v244, 7, v124
	v_lshl_add_u32 v244, v244, 2, 0
	ds_read2_b32 v[240:241], v244 offset1:32
	ds_read2_b32 v[242:243], v244 offset0:64 offset1:96
	v_fma_f32 v9, -v160, v238, v101
	v_fmac_f32_e32 v55, v9, v9
	v_fma_f32 v56, -v160, v239, v102
	v_fmac_f32_e32 v55, v56, v56
	s_nop 1
	v_mov_b32_dpp v57, v55 quad_perm:[1,0,3,2] row_mask:0xf bank_mask:0xf
	v_add_f32_e32 v55, v55, v57
	s_nop 1
	v_mov_b32_dpp v57, v55 quad_perm:[2,3,0,1] row_mask:0xf bank_mask:0xf
	v_add_f32_e32 v55, v55, v57
	s_nop 1
	v_mov_b32_dpp v57, v55 row_half_mirror row_mask:0xf bank_mask:0xf
	s_nop 1
	v_mov_b32_dpp v57, v57 quad_perm:[3,2,1,0] row_mask:0xf bank_mask:0xf
	v_add_f32_e32 v55, v55, v57
	s_nop 1
	v_mov_b32_dpp v57, v55 row_ror:8 row_mask:0xf bank_mask:0xf
	v_add_f32_e32 v55, v55, v57
	v_mov_b32_e32 v57, v55
	s_nop 1
	v_permlane16_swap_b32_e32 v55, v57
	v_add_f32_e32 v55, v55, v57
	v_fmamk_f32 v55, v55, 0x3c000000, v179
	v_cmp_gt_f32_e32 vcc, s4, v55
	v_mul_f32_e32 v57, 0x4f800000, v55
	s_nop 0
	v_cndmask_b32_e32 v55, v55, v57, vcc
	v_sqrt_f32_e32 v57, v55
	s_nop 0
	v_add_u32_e32 v59, -1, v57
	v_fma_f32 v60, -v59, v57, v55
	v_cmp_ge_f32_e64 s[0:1], 0, v60
	v_add_u32_e32 v60, 1, v57
	s_nop 0
	v_cndmask_b32_e64 v59, v57, v59, s[0:1]
	v_fma_f32 v57, -v60, v57, v55
	v_cmp_lt_f32_e64 s[0:1], 0, v57
	s_nop 1
	v_cndmask_b32_e64 v57, v59, v60, s[0:1]
	v_mul_f32_e32 v59, 0x37800000, v57
	v_cndmask_b32_e32 v57, v57, v59, vcc
	v_cmp_class_f32_e32 vcc, v55, v180
	s_nop 1
	v_cndmask_b32_e32 v55, v57, v55, vcc
	v_div_scale_f32 v57, s[0:1], v55, v55, 1.0
	v_rcp_f32_e32 v59, v57
	s_nop 0
	v_fma_f32 v60, -v57, v59, 1.0
	v_fmac_f32_e32 v59, v60, v59
	v_div_scale_f32 v60, vcc, 1.0, v55, 1.0
	v_mul_f32_e32 v61, v60, v59
	v_fma_f32 v62, -v57, v61, v60
	v_fmac_f32_e32 v61, v62, v59
	v_fma_f32 v57, -v57, v61, v60
	v_div_fmas_f32 v57, v57, v59, v61
	v_div_fixup_f32 v57, v57, v55, 1.0
	v_mul_f32_e32 v31, v31, v57
	v_ashrrev_i32_e32 v55, 31, v54
	v_mul_f32_e32 v31, v34, v31
	v_lshlrev_b64 v[54:55], 12, v[54:55]
	v_bfe_u32 v59, v31, 16, 1
	v_lshl_add_u64 v[54:55], v[4:5], 0, v[54:55]
	v_add3_u32 v31, v31, v59, s70
	global_store_short_d16_hi v[54:55], v31, off
	v_mul_f32_e32 v31, v58, v57
	v_mul_f32_e32 v31, v35, v31
	v_bfe_u32 v58, v31, 16, 1
	v_mul_f32_e32 v9, v9, v57
	v_add3_u32 v31, v31, v58, s70
	v_mul_f32_e32 v9, v36, v9
	global_store_short_d16_hi v[54:55], v31, off offset:64
	v_bfe_u32 v31, v9, 16, 1
	v_add3_u32 v9, v9, v31, s70
	global_store_short_d16_hi v[54:55], v9, off offset:128
	v_mul_f32_e32 v9, v56, v57
	v_mul_f32_e32 v9, v37, v9
	v_bfe_u32 v31, v9, 16, 1
	v_add3_u32 v9, v9, v31, s70
	global_store_short_d16_hi v[54:55], v9, off offset:192
	v_add_u32_e32 v9, v30, v8
	v_lshl_add_u32 v9, v9, 7, v124
	v_lshl_add_u32 v9, v9, 2, 0
	s_waitcnt lgkmcnt(1)
; __device__ __forceinline__ unsigned f2bf(float f) { unsigned u = __builtin_bit_cast(unsigned, f); return (u + 0x7fffu + ((u >> 16) & 1u)) >> 16; }
; __device__ __forceinline__ int crow(int r, int hi) { return (r & 3) + 8 * (r >> 2) + 4 * hi; }
; __device__ __forceinline__ void attn_unit(const bf16* __restrict__ Qb, const bf16* __restrict__ Kh, const bf16* __restrict__ Vh, int klat0, int nlt, int kctx0, int NT,
;                                           float lam, float post, const float* __restrict__ subw, bf16* __restrict__ Ob, char* lds) {
;     ...
;     for (int r = 0; r < 16; ++r) { const int orow = crow(r, hi_e); float v[4]; float ss = 0.f;
; #pragma unroll
;       for (int d0 = 0; d0 < 4; ++d0) { v[d0] = o[d0][r] - lam * X[(wq_e * 32 + orow) * 128 + d0 * 32 + r32_e]; ss += v[d0] * v[d0]; }
;       ss += __shfl_xor(ss, 1); ss += __shfl_xor(ss, 2); ss += __shfl_xor(ss, 4); ss += __shfl_xor(ss, 8); ss += __shfl_xor(ss, 16);
;       const float rs = 1.0f / sqrtf(ss * (1.0f / 128.0f) + LN_EPS);
; #pragma unroll
;       for (int d0 = 0; d0 < 4; ++d0) Ow[(long)orow * DM + d0 * 32 + r32_e] = (bf16)f2bf(v[d0] * rs * sw[d0]); }
	v_fma_f32 v56, -v160, v240, v98
	v_fma_f32 v57, -v160, v241, v99
	v_mul_f32_e32 v31, v57, v57
	v_fmac_f32_e32 v31, v56, v56
	s_waitcnt lgkmcnt(0)
	v_add_u32_e32 v244, v28, v8
	v_lshl_add_u32 v244, v244, 7, v124
	v_lshl_add_u32 v244, v244, 2, 0
	ds_read2_b32 v[236:237], v244 offset1:32
	ds_read2_b32 v[238:239], v244 offset0:64 offset1:96
	v_fma_f32 v9, -v160, v242, v97
	v_fmac_f32_e32 v31, v9, v9
	v_fma_f32 v53, -v160, v243, v53
	v_fmac_f32_e32 v31, v53, v53
	s_nop 1
	v_mov_b32_dpp v54, v31 quad_perm:[1,0,3,2] row_mask:0xf bank_mask:0xf
	v_add_f32_e32 v31, v31, v54
	s_nop 1
	v_mov_b32_dpp v54, v31 quad_perm:[2,3,0,1] row_mask:0xf bank_mask:0xf
	v_add_f32_e32 v31, v31, v54
	s_nop 1
	v_mov_b32_dpp v54, v31 row_half_mirror row_mask:0xf bank_mask:0xf
	s_nop 1
	v_mov_b32_dpp v54, v54 quad_perm:[3,2,1,0] row_mask:0xf bank_mask:0xf
	v_add_f32_e32 v31, v31, v54
	s_nop 1
	v_mov_b32_dpp v54, v31 row_ror:8 row_mask:0xf bank_mask:0xf
	v_add_f32_e32 v31, v31, v54
	v_mov_b32_e32 v54, v31
	s_nop 1
	v_permlane16_swap_b32_e32 v31, v54
	v_add_f32_e32 v31, v31, v54
	v_fmamk_f32 v31, v31, 0x3c000000, v179
	v_cmp_gt_f32_e32 vcc, s4, v31
	v_mul_f32_e32 v54, 0x4f800000, v31
	s_nop 0
	v_cndmask_b32_e32 v31, v31, v54, vcc
	v_sqrt_f32_e32 v54, v31
	s_nop 0
	v_add_u32_e32 v55, -1, v54
	v_fma_f32 v58, -v55, v54, v31
	v_cmp_ge_f32_e64 s[0:1], 0, v58
	v_add_u32_e32 v58, 1, v54
	s_nop 0
	v_cndmask_b32_e64 v55, v54, v55, s[0:1]
	v_fma_f32 v54, -v58, v54, v31
	v_cmp_lt_f32_e64 s[0:1], 0, v54
	s_nop 1
	v_cndmask_b32_e64 v54, v55, v58, s[0:1]
	v_mul_f32_e32 v55, 0x37800000, v54
	v_cndmask_b32_e32 v54, v54, v55, vcc
	v_cmp_class_f32_e32 vcc, v31, v180
	s_nop 1
	v_cndmask_b32_e32 v31, v54, v31, vcc
	v_div_scale_f32 v54, s[0:1], v31, v31, 1.0
	v_rcp_f32_e32 v55, v54
	s_nop 0
	v_fma_f32 v58, -v54, v55, 1.0
	v_fmac_f32_e32 v55, v58, v55
	v_div_scale_f32 v58, vcc, 1.0, v31, 1.0
	v_mul_f32_e32 v59, v58, v55
	v_fma_f32 v60, -v54, v59, v58
	v_fmac_f32_e32 v59, v60, v55
	v_fma_f32 v54, -v54, v59, v58
	v_div_fmas_f32 v54, v54, v55, v59
	v_div_fixup_f32 v54, v54, v31, 1.0
	v_mul_f32_e32 v55, v56, v54
	v_ashrrev_i32_e32 v31, 31, v30
	v_mul_f32_e32 v55, v34, v55
	v_lshlrev_b64 v[30:31], 12, v[30:31]
	v_bfe_u32 v56, v55, 16, 1
	v_lshl_add_u64 v[30:31], v[4:5], 0, v[30:31]
	v_add3_u32 v55, v55, v56, s70
	global_store_short_d16_hi v[30:31], v55, off
	v_mul_f32_e32 v55, v57, v54
	v_mul_f32_e32 v55, v35, v55
	v_bfe_u32 v56, v55, 16, 1
	v_mul_f32_e32 v9, v9, v54
	v_add3_u32 v55, v55, v56, s70
	v_mul_f32_e32 v9, v36, v9
	global_store_short_d16_hi v[30:31], v55, off offset:64
	v_bfe_u32 v55, v9, 16, 1
	v_add3_u32 v9, v9, v55, s70
	global_store_short_d16_hi v[30:31], v9, off offset:128
	v_mul_f32_e32 v9, v53, v54
	v_mul_f32_e32 v9, v37, v9
	v_bfe_u32 v53, v9, 16, 1
	v_add3_u32 v9, v9, v53, s70
	global_store_short_d16_hi v[30:31], v9, off offset:192
	v_add_u32_e32 v9, v28, v8
	v_lshl_add_u32 v9, v9, 7, v124
	v_lshl_add_u32 v9, v9, 2, 0
	v_lshlrev_b64 v[28:29], 12, v[28:29]
	v_lshl_add_u64 v[28:29], v[4:5], 0, v[28:29]
	s_waitcnt lgkmcnt(1)
	v_fma_f32 v53, -v160, v236, v95
	v_fma_f32 v54, -v160, v237, v96
	v_mul_f32_e32 v55, v54, v54
	v_fmac_f32_e32 v55, v53, v53
	s_waitcnt lgkmcnt(0)
	v_add_u32_e32 v244, v26, v8
	v_lshl_add_u32 v244, v244, 7, v124
	v_lshl_add_u32 v244, v244, 2, 0
	ds_read2_b32 v[240:241], v244 offset1:32
	ds_read2_b32 v[242:243], v244 offset0:64 offset1:96
	v_fma_f32 v9, -v160, v238, v94
	v_fmac_f32_e32 v55, v9, v9
	v_fma_f32 v30, -v160, v239, v52
	v_fmac_f32_e32 v55, v30, v30
	s_nop 1
	v_mov_b32_dpp v31, v55 quad_perm:[1,0,3,2] row_mask:0xf bank_mask:0xf
	v_add_f32_e32 v31, v55, v31
	s_nop 1
	v_mov_b32_dpp v52, v31 quad_perm:[2,3,0,1] row_mask:0xf bank_mask:0xf
	v_add_f32_e32 v31, v31, v52
	s_nop 1
	v_mov_b32_dpp v52, v31 row_half_mirror row_mask:0xf bank_mask:0xf
	s_nop 1
	v_mov_b32_dpp v52, v52 quad_perm:[3,2,1,0] row_mask:0xf bank_mask:0xf
	v_add_f32_e32 v31, v31, v52
	s_nop 1
	v_mov_b32_dpp v52, v31 row_ror:8 row_mask:0xf bank_mask:0xf
	v_add_f32_e32 v31, v31, v52
	v_mov_b32_e32 v52, v31
	s_nop 1
	v_permlane16_swap_b32_e32 v31, v52
	v_add_f32_e32 v31, v31, v52
	v_fmamk_f32 v31, v31, 0x3c000000, v179
	v_cmp_gt_f32_e32 vcc, s4, v31
	v_mul_f32_e32 v52, 0x4f800000, v31
	s_nop 0
	v_cndmask_b32_e32 v31, v31, v52, vcc
	v_sqrt_f32_e32 v52, v31
	s_nop 0
	v_add_u32_e32 v55, -1, v52
	v_fma_f32 v56, -v55, v52, v31
	v_cmp_ge_f32_e64 s[0:1], 0, v56
	v_add_u32_e32 v56, 1, v52
	s_nop 0
	v_cndmask_b32_e64 v55, v52, v55, s[0:1]
	v_fma_f32 v52, -v56, v52, v31
	v_cmp_lt_f32_e64 s[0:1], 0, v52
	s_nop 1
	v_cndmask_b32_e64 v52, v55, v56, s[0:1]
	v_mul_f32_e32 v55, 0x37800000, v52
	v_cndmask_b32_e32 v52, v52, v55, vcc
	v_cmp_class_f32_e32 vcc, v31, v180
	s_nop 1
	v_cndmask_b32_e32 v31, v52, v31, vcc
	v_div_scale_f32 v52, s[0:1], v31, v31, 1.0
	v_rcp_f32_e32 v55, v52
	s_nop 0
	v_fma_f32 v56, -v52, v55, 1.0
	v_fmac_f32_e32 v55, v56, v55
	v_div_scale_f32 v56, vcc, 1.0, v31, 1.0
	v_mul_f32_e32 v57, v56, v55
	v_fma_f32 v58, -v52, v57, v56
	v_fmac_f32_e32 v57, v58, v55
	v_fma_f32 v52, -v52, v57, v56
	v_div_fmas_f32 v52, v52, v55, v57
	v_div_fixup_f32 v31, v52, v31, 1.0
	v_mul_f32_e32 v52, v53, v31
	v_mul_f32_e32 v52, v34, v52
	v_bfe_u32 v53, v52, 16, 1
	v_add3_u32 v52, v52, v53, s70
	global_store_short_d16_hi v[28:29], v52, off
	v_mul_f32_e32 v52, v54, v31
	v_mul_f32_e32 v52, v35, v52
	v_bfe_u32 v53, v52, 16, 1
	v_mul_f32_e32 v9, v9, v31
	v_add3_u32 v52, v52, v53, s70
	v_mul_f32_e32 v9, v36, v9
	global_store_short_d16_hi v[28:29], v52, off offset:64
	v_bfe_u32 v52, v9, 16, 1
	v_add3_u32 v9, v9, v52, s70
	global_store_short_d16_hi v[28:29], v9, off offset:128
	v_mul_f32_e32 v9, v30, v31
	v_mul_f32_e32 v9, v37, v9
	v_bfe_u32 v30, v9, 16, 1
	v_add3_u32 v9, v9, v30, s70
	global_store_short_d16_hi v[28:29], v9, off offset:192
	v_add_u32_e32 v9, v26, v8
	v_lshl_add_u32 v9, v9, 7, v124
	v_lshl_add_u32 v9, v9, 2, 0
	v_lshlrev_b64 v[26:27], 12, v[26:27]
	v_lshl_add_u64 v[26:27], v[4:5], 0, v[26:27]
	s_waitcnt lgkmcnt(1)
; __device__ __forceinline__ unsigned f2bf(float f) { unsigned u = __builtin_bit_cast(unsigned, f); return (u + 0x7fffu + ((u >> 16) & 1u)) >> 16; }
; __device__ __forceinline__ int crow(int r, int hi) { return (r & 3) + 8 * (r >> 2) + 4 * hi; }
; __device__ __forceinline__ void attn_unit(const bf16* __restrict__ Qb, const bf16* __restrict__ Kh, const bf16* __restrict__ Vh, int klat0, int nlt, int kctx0, int NT,
;                                           float lam, float post, const float* __restrict__ subw, bf16* __restrict__ Ob, char* lds) {
;     ...
;     for (int r = 0; r < 16; ++r) { const int orow = crow(r, hi_e); float v[4]; float ss = 0.f;
; #pragma unroll
;       for (int d0 = 0; d0 < 4; ++d0) { v[d0] = o[d0][r] - lam * X[(wq_e * 32 + orow) * 128 + d0 * 32 + r32_e]; ss += v[d0] * v[d0]; }
;       ss += __shfl_xor(ss, 1); ss += __shfl_xor(ss, 2); ss += __shfl_xor(ss, 4); ss += __shfl_xor(ss, 8); ss += __shfl_xor(ss, 16);
;       const float rs = 1.0f / sqrtf(ss * (1.0f / 128.0f) + LN_EPS);
; #pragma unroll
;       for (int d0 = 0; d0 < 4; ++d0) Ow[(long)orow * DM + d0 * 32 + r32_e] = (bf16)f2bf(v[d0] * rs * sw[d0]); }
	v_fma_f32 v30, -v160, v240, v92
	v_fma_f32 v31, -v160, v241, v93
	v_mul_f32_e32 v52, v31, v31
	v_fmac_f32_e32 v52, v30, v30
	s_waitcnt lgkmcnt(0)
	v_add_u32_e32 v244, v24, v8
	v_lshl_add_u32 v244, v244, 7, v124
	v_lshl_add_u32 v244, v244, 2, 0
	ds_read2_b32 v[236:237], v244 offset1:32
	ds_read2_b32 v[238:239], v244 offset0:64 offset1:96
	v_fma_f32 v9, -v160, v242, v91
	v_fmac_f32_e32 v52, v9, v9
	v_fma_f32 v28, -v160, v243, v51
	v_fmac_f32_e32 v52, v28, v28
	s_nop 1
	v_mov_b32_dpp v29, v52 quad_perm:[1,0,3,2] row_mask:0xf bank_mask:0xf
	v_add_f32_e32 v29, v52, v29
	s_nop 1
	v_mov_b32_dpp v51, v29 quad_perm:[2,3,0,1] row_mask:0xf bank_mask:0xf
	v_add_f32_e32 v29, v29, v51
	s_nop 1
	v_mov_b32_dpp v51, v29 row_half_mirror row_mask:0xf bank_mask:0xf
	s_nop 1
	v_mov_b32_dpp v51, v51 quad_perm:[3,2,1,0] row_mask:0xf bank_mask:0xf
	v_add_f32_e32 v29, v29, v51
	s_nop 1
	v_mov_b32_dpp v51, v29 row_ror:8 row_mask:0xf bank_mask:0xf
	v_add_f32_e32 v29, v29, v51
	v_mov_b32_e32 v51, v29
	s_nop 1
	v_permlane16_swap_b32_e32 v29, v51
	v_add_f32_e32 v29, v29, v51
	v_fmamk_f32 v29, v29, 0x3c000000, v179
	v_cmp_gt_f32_e32 vcc, s4, v29
	v_mul_f32_e32 v51, 0x4f800000, v29
	s_nop 0
	v_cndmask_b32_e32 v29, v29, v51, vcc
	v_sqrt_f32_e32 v51, v29
	s_nop 0
	v_add_u32_e32 v52, -1, v51
	v_fma_f32 v53, -v52, v51, v29
	v_cmp_ge_f32_e64 s[0:1], 0, v53
	v_add_u32_e32 v53, 1, v51
	s_nop 0
	v_cndmask_b32_e64 v52, v51, v52, s[0:1]
	v_fma_f32 v51, -v53, v51, v29
	v_cmp_lt_f32_e64 s[0:1], 0, v51
	s_nop 1
	v_cndmask_b32_e64 v51, v52, v53, s[0:1]
	v_mul_f32_e32 v52, 0x37800000, v51
	v_cndmask_b32_e32 v51, v51, v52, vcc
	v_cmp_class_f32_e32 vcc, v29, v180
	s_nop 1
	v_cndmask_b32_e32 v29, v51, v29, vcc
	v_div_scale_f32 v51, s[0:1], v29, v29, 1.0
	v_rcp_f32_e32 v52, v51
	s_nop 0
	v_fma_f32 v53, -v51, v52, 1.0
	v_fmac_f32_e32 v52, v53, v52
	v_div_scale_f32 v53, vcc, 1.0, v29, 1.0
	v_mul_f32_e32 v54, v53, v52
	v_fma_f32 v55, -v51, v54, v53
	v_fmac_f32_e32 v54, v55, v52
	v_fma_f32 v51, -v51, v54, v53
	v_div_fmas_f32 v51, v51, v52, v54
	v_div_fixup_f32 v29, v51, v29, 1.0
	v_mul_f32_e32 v30, v30, v29
	v_mul_f32_e32 v30, v34, v30
	v_bfe_u32 v51, v30, 16, 1
	v_add3_u32 v30, v30, v51, s70
	global_store_short_d16_hi v[26:27], v30, off
	v_mul_f32_e32 v30, v31, v29
	v_mul_f32_e32 v30, v35, v30
	v_bfe_u32 v31, v30, 16, 1
	v_mul_f32_e32 v9, v9, v29
	v_add3_u32 v30, v30, v31, s70
	v_mul_f32_e32 v9, v36, v9
	global_store_short_d16_hi v[26:27], v30, off offset:64
	v_bfe_u32 v30, v9, 16, 1
	v_add3_u32 v9, v9, v30, s70
	global_store_short_d16_hi v[26:27], v9, off offset:128
	v_mul_f32_e32 v9, v28, v29
	v_mul_f32_e32 v9, v37, v9
	v_bfe_u32 v28, v9, 16, 1
	v_add3_u32 v9, v9, v28, s70
	global_store_short_d16_hi v[26:27], v9, off offset:192
	v_add_u32_e32 v9, v24, v8
	v_lshl_add_u32 v9, v9, 7, v124
	v_lshl_add_u32 v9, v9, 2, 0
	v_lshlrev_b64 v[24:25], 12, v[24:25]
	v_lshl_add_u64 v[24:25], v[4:5], 0, v[24:25]
	s_waitcnt lgkmcnt(1)
	v_fma_f32 v28, -v160, v236, v89
	v_fma_f32 v29, -v160, v237, v90
	v_mul_f32_e32 v30, v29, v29
	v_fmac_f32_e32 v30, v28, v28
	s_waitcnt lgkmcnt(0)
	v_add_u32_e32 v244, v22, v8
	v_lshl_add_u32 v244, v244, 7, v124
	v_lshl_add_u32 v244, v244, 2, 0
	ds_read2_b32 v[240:241], v244 offset1:32
	ds_read2_b32 v[242:243], v244 offset0:64 offset1:96
	v_fma_f32 v9, -v160, v238, v88
	v_fmac_f32_e32 v30, v9, v9
	v_fma_f32 v26, -v160, v239, v50
	v_fmac_f32_e32 v30, v26, v26
	s_nop 1
	v_mov_b32_dpp v27, v30 quad_perm:[1,0,3,2] row_mask:0xf bank_mask:0xf
	v_add_f32_e32 v27, v30, v27
	s_nop 1
	v_mov_b32_dpp v30, v27 quad_perm:[2,3,0,1] row_mask:0xf bank_mask:0xf
	v_add_f32_e32 v27, v27, v30
	s_nop 1
	v_mov_b32_dpp v30, v27 row_half_mirror row_mask:0xf bank_mask:0xf
	s_nop 1
	v_mov_b32_dpp v30, v30 quad_perm:[3,2,1,0] row_mask:0xf bank_mask:0xf
	v_add_f32_e32 v27, v27, v30
	s_nop 1
	v_mov_b32_dpp v30, v27 row_ror:8 row_mask:0xf bank_mask:0xf
	v_add_f32_e32 v27, v27, v30
	v_mov_b32_e32 v30, v27
	s_nop 1
	v_permlane16_swap_b32_e32 v27, v30
	v_add_f32_e32 v27, v27, v30
	v_fmamk_f32 v27, v27, 0x3c000000, v179
	v_cmp_gt_f32_e32 vcc, s4, v27
	v_mul_f32_e32 v30, 0x4f800000, v27
	s_nop 0
	v_cndmask_b32_e32 v27, v27, v30, vcc
	v_sqrt_f32_e32 v30, v27
	s_nop 0
	v_add_u32_e32 v31, -1, v30
	v_fma_f32 v50, -v31, v30, v27
	v_cmp_ge_f32_e64 s[0:1], 0, v50
	v_add_u32_e32 v50, 1, v30
	s_nop 0
	v_cndmask_b32_e64 v31, v30, v31, s[0:1]
	v_fma_f32 v30, -v50, v30, v27
	v_cmp_lt_f32_e64 s[0:1], 0, v30
	s_nop 1
	v_cndmask_b32_e64 v30, v31, v50, s[0:1]
	v_mul_f32_e32 v31, 0x37800000, v30
	v_cndmask_b32_e32 v30, v30, v31, vcc
	v_cmp_class_f32_e32 vcc, v27, v180
	s_nop 1
	v_cndmask_b32_e32 v27, v30, v27, vcc
	v_div_scale_f32 v30, s[0:1], v27, v27, 1.0
	v_rcp_f32_e32 v31, v30
	s_nop 0
	v_fma_f32 v50, -v30, v31, 1.0
	v_fmac_f32_e32 v31, v50, v31
	v_div_scale_f32 v50, vcc, 1.0, v27, 1.0
	v_mul_f32_e32 v51, v50, v31
	v_fma_f32 v52, -v30, v51, v50
	v_fmac_f32_e32 v51, v52, v31
	v_fma_f32 v30, -v30, v51, v50
	v_div_fmas_f32 v30, v30, v31, v51
	v_div_fixup_f32 v27, v30, v27, 1.0
	v_mul_f32_e32 v28, v28, v27
	v_mul_f32_e32 v28, v34, v28
	v_bfe_u32 v30, v28, 16, 1
	v_add3_u32 v28, v28, v30, s70
	global_store_short_d16_hi v[24:25], v28, off
	v_mul_f32_e32 v28, v29, v27
	v_mul_f32_e32 v28, v35, v28
	v_bfe_u32 v29, v28, 16, 1
	v_mul_f32_e32 v9, v9, v27
	v_add3_u32 v28, v28, v29, s70
	v_mul_f32_e32 v9, v36, v9
	global_store_short_d16_hi v[24:25], v28, off offset:64
	v_bfe_u32 v28, v9, 16, 1
	v_add3_u32 v9, v9, v28, s70
	global_store_short_d16_hi v[24:25], v9, off offset:128
	v_mul_f32_e32 v9, v26, v27
	v_mul_f32_e32 v9, v37, v9
	v_bfe_u32 v26, v9, 16, 1
	v_add3_u32 v9, v9, v26, s70
	global_store_short_d16_hi v[24:25], v9, off offset:192
	v_add_u32_e32 v9, v22, v8
	v_lshl_add_u32 v9, v9, 7, v124
	v_lshl_add_u32 v9, v9, 2, 0
	v_lshlrev_b64 v[22:23], 12, v[22:23]
	v_lshl_add_u64 v[22:23], v[4:5], 0, v[22:23]
	s_waitcnt lgkmcnt(1)
; __device__ __forceinline__ unsigned f2bf(float f) { unsigned u = __builtin_bit_cast(unsigned, f); return (u + 0x7fffu + ((u >> 16) & 1u)) >> 16; }
; __device__ __forceinline__ int crow(int r, int hi) { return (r & 3) + 8 * (r >> 2) + 4 * hi; }
; __device__ __forceinline__ void attn_unit(const bf16* __restrict__ Qb, const bf16* __restrict__ Kh, const bf16* __restrict__ Vh, int klat0, int nlt, int kctx0, int NT,
;                                           float lam, float post, const float* __restrict__ subw, bf16* __restrict__ Ob, char* lds) {
;     ...
;     for (int r = 0; r < 16; ++r) { const int orow = crow(r, hi_e); float v[4]; float ss = 0.f;
; #pragma unroll
;       for (int d0 = 0; d0 < 4; ++d0) { v[d0] = o[d0][r] - lam * X[(wq_e * 32 + orow) * 128 + d0 * 32 + r32_e]; ss += v[d0] * v[d0]; }
;       ss += __shfl_xor(ss, 1); ss += __shfl_xor(ss, 2); ss += __shfl_xor(ss, 4); ss += __shfl_xor(ss, 8); ss += __shfl_xor(ss, 16);
;       const float rs = 1.0f / sqrtf(ss * (1.0f / 128.0f) + LN_EPS);
; #pragma unroll
;       for (int d0 = 0; d0 < 4; ++d0) Ow[(long)orow * DM + d0 * 32 + r32_e] = (bf16)f2bf(v[d0] * rs * sw[d0]); }
	v_fma_f32 v26, -v160, v240, v86
	v_fma_f32 v27, -v160, v241, v87
	v_mul_f32_e32 v28, v27, v27
	v_fmac_f32_e32 v28, v26, v26
	s_waitcnt lgkmcnt(0)
	v_add_u32_e32 v244, v20, v8
	v_lshl_add_u32 v244, v244, 7, v124
	v_lshl_add_u32 v244, v244, 2, 0
	ds_read2_b32 v[236:237], v244 offset1:32
	ds_read2_b32 v[238:239], v244 offset0:64 offset1:96
	v_fma_f32 v9, -v160, v242, v85
	v_fmac_f32_e32 v28, v9, v9
	v_fma_f32 v24, -v160, v243, v49
	v_fmac_f32_e32 v28, v24, v24
	s_nop 1
	v_mov_b32_dpp v25, v28 quad_perm:[1,0,3,2] row_mask:0xf bank_mask:0xf
	v_add_f32_e32 v25, v28, v25
	s_nop 1
	v_mov_b32_dpp v28, v25 quad_perm:[2,3,0,1] row_mask:0xf bank_mask:0xf
	v_add_f32_e32 v25, v25, v28
	s_nop 1
	v_mov_b32_dpp v28, v25 row_half_mirror row_mask:0xf bank_mask:0xf
	s_nop 1
	v_mov_b32_dpp v28, v28 quad_perm:[3,2,1,0] row_mask:0xf bank_mask:0xf
	v_add_f32_e32 v25, v25, v28
	s_nop 1
	v_mov_b32_dpp v28, v25 row_ror:8 row_mask:0xf bank_mask:0xf
	v_add_f32_e32 v25, v25, v28
	v_mov_b32_e32 v28, v25
	s_nop 1
	v_permlane16_swap_b32_e32 v25, v28
	v_add_f32_e32 v25, v25, v28
	v_fmamk_f32 v25, v25, 0x3c000000, v179
	v_cmp_gt_f32_e32 vcc, s4, v25
	v_mul_f32_e32 v28, 0x4f800000, v25
	s_nop 0
	v_cndmask_b32_e32 v25, v25, v28, vcc
	v_sqrt_f32_e32 v28, v25
	s_nop 0
	v_add_u32_e32 v29, -1, v28
	v_fma_f32 v30, -v29, v28, v25
	v_cmp_ge_f32_e64 s[0:1], 0, v30
	v_add_u32_e32 v30, 1, v28
	s_nop 0
	v_cndmask_b32_e64 v29, v28, v29, s[0:1]
	v_fma_f32 v28, -v30, v28, v25
	v_cmp_lt_f32_e64 s[0:1], 0, v28
	s_nop 1
	v_cndmask_b32_e64 v28, v29, v30, s[0:1]
	v_mul_f32_e32 v29, 0x37800000, v28
	v_cndmask_b32_e32 v28, v28, v29, vcc
	v_cmp_class_f32_e32 vcc, v25, v180
	s_nop 1
	v_cndmask_b32_e32 v25, v28, v25, vcc
	v_div_scale_f32 v28, s[0:1], v25, v25, 1.0
	v_rcp_f32_e32 v29, v28
	s_nop 0
	v_fma_f32 v30, -v28, v29, 1.0
	v_fmac_f32_e32 v29, v30, v29
	v_div_scale_f32 v30, vcc, 1.0, v25, 1.0
	v_mul_f32_e32 v31, v30, v29
	v_fma_f32 v49, -v28, v31, v30
	v_fmac_f32_e32 v31, v49, v29
	v_fma_f32 v28, -v28, v31, v30
	v_div_fmas_f32 v28, v28, v29, v31
	v_div_fixup_f32 v25, v28, v25, 1.0
	v_mul_f32_e32 v26, v26, v25
	v_mul_f32_e32 v26, v34, v26
	v_bfe_u32 v28, v26, 16, 1
	v_add3_u32 v26, v26, v28, s70
	global_store_short_d16_hi v[22:23], v26, off
	v_mul_f32_e32 v26, v27, v25
	v_mul_f32_e32 v26, v35, v26
	v_bfe_u32 v27, v26, 16, 1
	v_mul_f32_e32 v9, v9, v25
	v_add3_u32 v26, v26, v27, s70
	v_mul_f32_e32 v9, v36, v9
	global_store_short_d16_hi v[22:23], v26, off offset:64
	v_bfe_u32 v26, v9, 16, 1
	v_add3_u32 v9, v9, v26, s70
	global_store_short_d16_hi v[22:23], v9, off offset:128
	v_mul_f32_e32 v9, v24, v25
	v_mul_f32_e32 v9, v37, v9
	v_bfe_u32 v24, v9, 16, 1
	v_add3_u32 v9, v9, v24, s70
	global_store_short_d16_hi v[22:23], v9, off offset:192
	v_add_u32_e32 v9, v20, v8
	v_lshl_add_u32 v9, v9, 7, v124
	v_lshl_add_u32 v9, v9, 2, 0
	v_lshlrev_b64 v[20:21], 12, v[20:21]
	v_lshl_add_u64 v[20:21], v[4:5], 0, v[20:21]
	s_waitcnt lgkmcnt(1)
	v_fma_f32 v24, -v160, v236, v83
	v_fma_f32 v25, -v160, v237, v84
	v_mul_f32_e32 v26, v25, v25
	v_fmac_f32_e32 v26, v24, v24
	s_waitcnt lgkmcnt(0)
	v_add_u32_e32 v244, v18, v8
	v_lshl_add_u32 v244, v244, 7, v124
	v_lshl_add_u32 v244, v244, 2, 0
	ds_read2_b32 v[240:241], v244 offset1:32
	ds_read2_b32 v[242:243], v244 offset0:64 offset1:96
	v_fma_f32 v9, -v160, v238, v82
	v_fmac_f32_e32 v26, v9, v9
	v_fma_f32 v22, -v160, v239, v48
	v_fmac_f32_e32 v26, v22, v22
	s_nop 1
	v_mov_b32_dpp v23, v26 quad_perm:[1,0,3,2] row_mask:0xf bank_mask:0xf
	v_add_f32_e32 v23, v26, v23
	s_nop 1
	v_mov_b32_dpp v26, v23 quad_perm:[2,3,0,1] row_mask:0xf bank_mask:0xf
	v_add_f32_e32 v23, v23, v26
	s_nop 1
	v_mov_b32_dpp v26, v23 row_half_mirror row_mask:0xf bank_mask:0xf
	s_nop 1
	v_mov_b32_dpp v26, v26 quad_perm:[3,2,1,0] row_mask:0xf bank_mask:0xf
	v_add_f32_e32 v23, v23, v26
	s_nop 1
	v_mov_b32_dpp v26, v23 row_ror:8 row_mask:0xf bank_mask:0xf
	v_add_f32_e32 v23, v23, v26
	v_mov_b32_e32 v26, v23
	s_nop 1
	v_permlane16_swap_b32_e32 v23, v26
	v_add_f32_e32 v23, v23, v26
	v_fmamk_f32 v23, v23, 0x3c000000, v179
	v_cmp_gt_f32_e32 vcc, s4, v23
	v_mul_f32_e32 v26, 0x4f800000, v23
	s_nop 0
	v_cndmask_b32_e32 v23, v23, v26, vcc
	v_sqrt_f32_e32 v26, v23
	s_nop 0
	v_add_u32_e32 v27, -1, v26
	v_fma_f32 v28, -v27, v26, v23
	v_cmp_ge_f32_e64 s[0:1], 0, v28
	v_add_u32_e32 v28, 1, v26
	s_nop 0
	v_cndmask_b32_e64 v27, v26, v27, s[0:1]
	v_fma_f32 v26, -v28, v26, v23
	v_cmp_lt_f32_e64 s[0:1], 0, v26
	s_nop 1
	v_cndmask_b32_e64 v26, v27, v28, s[0:1]
	v_mul_f32_e32 v27, 0x37800000, v26
	v_cndmask_b32_e32 v26, v26, v27, vcc
	v_cmp_class_f32_e32 vcc, v23, v180
	s_nop 1
	v_cndmask_b32_e32 v23, v26, v23, vcc
	v_div_scale_f32 v26, s[0:1], v23, v23, 1.0
	v_rcp_f32_e32 v27, v26
	s_nop 0
	v_fma_f32 v28, -v26, v27, 1.0
	v_fmac_f32_e32 v27, v28, v27
	v_div_scale_f32 v28, vcc, 1.0, v23, 1.0
	v_mul_f32_e32 v29, v28, v27
	v_fma_f32 v30, -v26, v29, v28
	v_fmac_f32_e32 v29, v30, v27
	v_fma_f32 v26, -v26, v29, v28
	v_div_fmas_f32 v26, v26, v27, v29
	v_div_fixup_f32 v23, v26, v23, 1.0
	v_mul_f32_e32 v24, v24, v23
	v_mul_f32_e32 v24, v34, v24
	v_bfe_u32 v26, v24, 16, 1
	v_add3_u32 v24, v24, v26, s70
	global_store_short_d16_hi v[20:21], v24, off
	v_mul_f32_e32 v24, v25, v23
	v_mul_f32_e32 v24, v35, v24
	v_bfe_u32 v25, v24, 16, 1
	v_mul_f32_e32 v9, v9, v23
	v_add3_u32 v24, v24, v25, s70
	v_mul_f32_e32 v9, v36, v9
	global_store_short_d16_hi v[20:21], v24, off offset:64
	v_bfe_u32 v24, v9, 16, 1
	v_add3_u32 v9, v9, v24, s70
	global_store_short_d16_hi v[20:21], v9, off offset:128
	v_mul_f32_e32 v9, v22, v23
	v_mul_f32_e32 v9, v37, v9
	v_bfe_u32 v22, v9, 16, 1
	v_add3_u32 v9, v9, v22, s70
	global_store_short_d16_hi v[20:21], v9, off offset:192
	v_add_u32_e32 v9, v18, v8
	v_lshl_add_u32 v9, v9, 7, v124
	v_lshl_add_u32 v9, v9, 2, 0
	v_lshlrev_b64 v[18:19], 12, v[18:19]
	v_lshl_add_u64 v[18:19], v[4:5], 0, v[18:19]
	s_waitcnt lgkmcnt(1)
; __device__ __forceinline__ unsigned f2bf(float f) { unsigned u = __builtin_bit_cast(unsigned, f); return (u + 0x7fffu + ((u >> 16) & 1u)) >> 16; }
; __device__ __forceinline__ int crow(int r, int hi) { return (r & 3) + 8 * (r >> 2) + 4 * hi; }
; __device__ __forceinline__ void attn_unit(const bf16* __restrict__ Qb, const bf16* __restrict__ Kh, const bf16* __restrict__ Vh, int klat0, int nlt, int kctx0, int NT,
;                                           float lam, float post, const float* __restrict__ subw, bf16* __restrict__ Ob, char* lds) {
;     ...
;     for (int r = 0; r < 16; ++r) { const int orow = crow(r, hi_e); float v[4]; float ss = 0.f;
; #pragma unroll
;       for (int d0 = 0; d0 < 4; ++d0) { v[d0] = o[d0][r] - lam * X[(wq_e * 32 + orow) * 128 + d0 * 32 + r32_e]; ss += v[d0] * v[d0]; }
;       ss += __shfl_xor(ss, 1); ss += __shfl_xor(ss, 2); ss += __shfl_xor(ss, 4); ss += __shfl_xor(ss, 8); ss += __shfl_xor(ss, 16);
;       const float rs = 1.0f / sqrtf(ss * (1.0f / 128.0f) + LN_EPS);
; #pragma unroll
;       for (int d0 = 0; d0 < 4; ++d0) Ow[(long)orow * DM + d0 * 32 + r32_e] = (bf16)f2bf(v[d0] * rs * sw[d0]); }
	v_fma_f32 v22, -v160, v240, v80
	v_fma_f32 v23, -v160, v241, v81
	v_mul_f32_e32 v24, v23, v23
	v_fmac_f32_e32 v24, v22, v22
	s_waitcnt lgkmcnt(0)
	v_add_u32_e32 v244, v16, v8
	v_lshl_add_u32 v244, v244, 7, v124
	v_lshl_add_u32 v244, v244, 2, 0
	ds_read2_b32 v[236:237], v244 offset1:32
	ds_read2_b32 v[238:239], v244 offset0:64 offset1:96
	v_fma_f32 v9, -v160, v242, v79
	v_fmac_f32_e32 v24, v9, v9
	v_fma_f32 v20, -v160, v243, v47
	v_fmac_f32_e32 v24, v20, v20
	s_nop 1
	v_mov_b32_dpp v21, v24 quad_perm:[1,0,3,2] row_mask:0xf bank_mask:0xf
	v_add_f32_e32 v21, v24, v21
	s_nop 1
	v_mov_b32_dpp v24, v21 quad_perm:[2,3,0,1] row_mask:0xf bank_mask:0xf
	v_add_f32_e32 v21, v21, v24
	s_nop 1
	v_mov_b32_dpp v24, v21 row_half_mirror row_mask:0xf bank_mask:0xf
	s_nop 1
	v_mov_b32_dpp v24, v24 quad_perm:[3,2,1,0] row_mask:0xf bank_mask:0xf
	v_add_f32_e32 v21, v21, v24
	s_nop 1
	v_mov_b32_dpp v24, v21 row_ror:8 row_mask:0xf bank_mask:0xf
	v_add_f32_e32 v21, v21, v24
	v_mov_b32_e32 v24, v21
	s_nop 1
	v_permlane16_swap_b32_e32 v21, v24
	v_add_f32_e32 v21, v21, v24
	v_fmamk_f32 v21, v21, 0x3c000000, v179
	v_cmp_gt_f32_e32 vcc, s4, v21
	v_mul_f32_e32 v24, 0x4f800000, v21
	s_nop 0
	v_cndmask_b32_e32 v21, v21, v24, vcc
	v_sqrt_f32_e32 v24, v21
	s_nop 0
	v_add_u32_e32 v25, -1, v24
	v_fma_f32 v26, -v25, v24, v21
	v_cmp_ge_f32_e64 s[0:1], 0, v26
	v_add_u32_e32 v26, 1, v24
	s_nop 0
	v_cndmask_b32_e64 v25, v24, v25, s[0:1]
	v_fma_f32 v24, -v26, v24, v21
	v_cmp_lt_f32_e64 s[0:1], 0, v24
	s_nop 1
	v_cndmask_b32_e64 v24, v25, v26, s[0:1]
	v_mul_f32_e32 v25, 0x37800000, v24
	v_cndmask_b32_e32 v24, v24, v25, vcc
	v_cmp_class_f32_e32 vcc, v21, v180
	s_nop 1
	v_cndmask_b32_e32 v21, v24, v21, vcc
	v_div_scale_f32 v24, s[0:1], v21, v21, 1.0
	v_rcp_f32_e32 v25, v24
	s_nop 0
	v_fma_f32 v26, -v24, v25, 1.0
	v_fmac_f32_e32 v25, v26, v25
	v_div_scale_f32 v26, vcc, 1.0, v21, 1.0
	v_mul_f32_e32 v27, v26, v25
	v_fma_f32 v28, -v24, v27, v26
	v_fmac_f32_e32 v27, v28, v25
	v_fma_f32 v24, -v24, v27, v26
	v_div_fmas_f32 v24, v24, v25, v27
	v_div_fixup_f32 v21, v24, v21, 1.0
	v_mul_f32_e32 v22, v22, v21
	v_mul_f32_e32 v22, v34, v22
	v_bfe_u32 v24, v22, 16, 1
	v_add3_u32 v22, v22, v24, s70
	global_store_short_d16_hi v[18:19], v22, off
	v_mul_f32_e32 v22, v23, v21
	v_mul_f32_e32 v22, v35, v22
	v_bfe_u32 v23, v22, 16, 1
	v_mul_f32_e32 v9, v9, v21
	v_add3_u32 v22, v22, v23, s70
	v_mul_f32_e32 v9, v36, v9
	global_store_short_d16_hi v[18:19], v22, off offset:64
	v_bfe_u32 v22, v9, 16, 1
	v_add3_u32 v9, v9, v22, s70
	global_store_short_d16_hi v[18:19], v9, off offset:128
	v_mul_f32_e32 v9, v20, v21
	v_mul_f32_e32 v9, v37, v9
	v_bfe_u32 v20, v9, 16, 1
	v_add3_u32 v9, v9, v20, s70
	global_store_short_d16_hi v[18:19], v9, off offset:192
	v_add_u32_e32 v9, v16, v8
	v_lshl_add_u32 v9, v9, 7, v124
	v_lshl_add_u32 v9, v9, 2, 0
	v_lshlrev_b64 v[16:17], 12, v[16:17]
	v_lshl_add_u64 v[16:17], v[4:5], 0, v[16:17]
	s_waitcnt lgkmcnt(1)
	v_fma_f32 v20, -v160, v236, v77
	v_fma_f32 v21, -v160, v237, v78
	v_mul_f32_e32 v22, v21, v21
	v_fmac_f32_e32 v22, v20, v20
	s_waitcnt lgkmcnt(0)
	v_add_u32_e32 v244, v14, v8
	v_lshl_add_u32 v244, v244, 7, v124
	v_lshl_add_u32 v244, v244, 2, 0
	ds_read2_b32 v[240:241], v244 offset1:32
	ds_read2_b32 v[242:243], v244 offset0:64 offset1:96
	v_fma_f32 v9, -v160, v238, v76
	v_fmac_f32_e32 v22, v9, v9
	v_fma_f32 v18, -v160, v239, v46
	v_fmac_f32_e32 v22, v18, v18
	s_nop 1
	v_mov_b32_dpp v19, v22 quad_perm:[1,0,3,2] row_mask:0xf bank_mask:0xf
	v_add_f32_e32 v19, v22, v19
	s_nop 1
	v_mov_b32_dpp v22, v19 quad_perm:[2,3,0,1] row_mask:0xf bank_mask:0xf
	v_add_f32_e32 v19, v19, v22
	s_nop 1
	v_mov_b32_dpp v22, v19 row_half_mirror row_mask:0xf bank_mask:0xf
	s_nop 1
	v_mov_b32_dpp v22, v22 quad_perm:[3,2,1,0] row_mask:0xf bank_mask:0xf
	v_add_f32_e32 v19, v19, v22
	s_nop 1
	v_mov_b32_dpp v22, v19 row_ror:8 row_mask:0xf bank_mask:0xf
	v_add_f32_e32 v19, v19, v22
	v_mov_b32_e32 v22, v19
	s_nop 1
	v_permlane16_swap_b32_e32 v19, v22
	v_add_f32_e32 v19, v19, v22
	v_fmamk_f32 v19, v19, 0x3c000000, v179
	v_cmp_gt_f32_e32 vcc, s4, v19
	v_mul_f32_e32 v22, 0x4f800000, v19
	s_nop 0
	v_cndmask_b32_e32 v19, v19, v22, vcc
	v_sqrt_f32_e32 v22, v19
	s_nop 0
	v_add_u32_e32 v23, -1, v22
	v_fma_f32 v24, -v23, v22, v19
	v_cmp_ge_f32_e64 s[0:1], 0, v24
	v_add_u32_e32 v24, 1, v22
	s_nop 0
	v_cndmask_b32_e64 v23, v22, v23, s[0:1]
	v_fma_f32 v22, -v24, v22, v19
	v_cmp_lt_f32_e64 s[0:1], 0, v22
	s_nop 1
	v_cndmask_b32_e64 v22, v23, v24, s[0:1]
	v_mul_f32_e32 v23, 0x37800000, v22
	v_cndmask_b32_e32 v22, v22, v23, vcc
	v_cmp_class_f32_e32 vcc, v19, v180
	s_nop 1
	v_cndmask_b32_e32 v19, v22, v19, vcc
	v_div_scale_f32 v22, s[0:1], v19, v19, 1.0
	v_rcp_f32_e32 v23, v22
	s_nop 0
	v_fma_f32 v24, -v22, v23, 1.0
	v_fmac_f32_e32 v23, v24, v23
	v_div_scale_f32 v24, vcc, 1.0, v19, 1.0
	v_mul_f32_e32 v25, v24, v23
	v_fma_f32 v26, -v22, v25, v24
	v_fmac_f32_e32 v25, v26, v23
	v_fma_f32 v22, -v22, v25, v24
	v_div_fmas_f32 v22, v22, v23, v25
	v_div_fixup_f32 v19, v22, v19, 1.0
	v_mul_f32_e32 v20, v20, v19
	v_mul_f32_e32 v20, v34, v20
	v_bfe_u32 v22, v20, 16, 1
	v_add3_u32 v20, v20, v22, s70
	global_store_short_d16_hi v[16:17], v20, off
	v_mul_f32_e32 v20, v21, v19
	v_mul_f32_e32 v20, v35, v20
	v_bfe_u32 v21, v20, 16, 1
	v_mul_f32_e32 v9, v9, v19
	v_add3_u32 v20, v20, v21, s70
	v_mul_f32_e32 v9, v36, v9
	global_store_short_d16_hi v[16:17], v20, off offset:64
	v_bfe_u32 v20, v9, 16, 1
	v_add3_u32 v9, v9, v20, s70
	global_store_short_d16_hi v[16:17], v9, off offset:128
	v_mul_f32_e32 v9, v18, v19
	v_mul_f32_e32 v9, v37, v9
	v_bfe_u32 v18, v9, 16, 1
	v_add3_u32 v9, v9, v18, s70
	global_store_short_d16_hi v[16:17], v9, off offset:192
	v_add_u32_e32 v9, v14, v8
	v_lshl_add_u32 v9, v9, 7, v124
	v_lshl_add_u32 v9, v9, 2, 0
	v_lshlrev_b64 v[14:15], 12, v[14:15]
	v_lshl_add_u64 v[14:15], v[4:5], 0, v[14:15]
	s_waitcnt lgkmcnt(1)
; __device__ __forceinline__ unsigned f2bf(float f) { unsigned u = __builtin_bit_cast(unsigned, f); return (u + 0x7fffu + ((u >> 16) & 1u)) >> 16; }
; __device__ __forceinline__ int crow(int r, int hi) { return (r & 3) + 8 * (r >> 2) + 4 * hi; }
; __device__ __forceinline__ void attn_unit(const bf16* __restrict__ Qb, const bf16* __restrict__ Kh, const bf16* __restrict__ Vh, int klat0, int nlt, int kctx0, int NT,
;                                           float lam, float post, const float* __restrict__ subw, bf16* __restrict__ Ob, char* lds) {
;     ...
;     for (int r = 0; r < 16; ++r) { const int orow = crow(r, hi_e); float v[4]; float ss = 0.f;
; #pragma unroll
;       for (int d0 = 0; d0 < 4; ++d0) { v[d0] = o[d0][r] - lam * X[(wq_e * 32 + orow) * 128 + d0 * 32 + r32_e]; ss += v[d0] * v[d0]; }
;       ss += __shfl_xor(ss, 1); ss += __shfl_xor(ss, 2); ss += __shfl_xor(ss, 4); ss += __shfl_xor(ss, 8); ss += __shfl_xor(ss, 16);
;       const float rs = 1.0f / sqrtf(ss * (1.0f / 128.0f) + LN_EPS);
; #pragma unroll
;       for (int d0 = 0; d0 < 4; ++d0) Ow[(long)orow * DM + d0 * 32 + r32_e] = (bf16)f2bf(v[d0] * rs * sw[d0]); }
	v_fma_f32 v18, -v160, v240, v74
	v_fma_f32 v19, -v160, v241, v75
	v_mul_f32_e32 v20, v19, v19
	v_fmac_f32_e32 v20, v18, v18
	s_waitcnt lgkmcnt(0)
	v_add_u32_e32 v244, v12, v8
	v_lshl_add_u32 v244, v244, 7, v124
	v_lshl_add_u32 v244, v244, 2, 0
	ds_read2_b32 v[236:237], v244 offset1:32
	ds_read2_b32 v[238:239], v244 offset0:64 offset1:96
	v_fma_f32 v9, -v160, v242, v44
	v_fmac_f32_e32 v20, v9, v9
	v_fma_f32 v16, -v160, v243, v45
	v_fmac_f32_e32 v20, v16, v16
	s_nop 1
	v_mov_b32_dpp v17, v20 quad_perm:[1,0,3,2] row_mask:0xf bank_mask:0xf
	v_add_f32_e32 v17, v20, v17
	s_nop 1
	v_mov_b32_dpp v20, v17 quad_perm:[2,3,0,1] row_mask:0xf bank_mask:0xf
	v_add_f32_e32 v17, v17, v20
	s_nop 1
	v_mov_b32_dpp v20, v17 row_half_mirror row_mask:0xf bank_mask:0xf
	s_nop 1
	v_mov_b32_dpp v20, v20 quad_perm:[3,2,1,0] row_mask:0xf bank_mask:0xf
	v_add_f32_e32 v17, v17, v20
	s_nop 1
	v_mov_b32_dpp v20, v17 row_ror:8 row_mask:0xf bank_mask:0xf
	v_add_f32_e32 v17, v17, v20
	v_mov_b32_e32 v20, v17
	s_nop 1
	v_permlane16_swap_b32_e32 v17, v20
	v_add_f32_e32 v17, v17, v20
	v_fmamk_f32 v17, v17, 0x3c000000, v179
	v_cmp_gt_f32_e32 vcc, s4, v17
	v_mul_f32_e32 v20, 0x4f800000, v17
	s_nop 0
	v_cndmask_b32_e32 v17, v17, v20, vcc
	v_sqrt_f32_e32 v20, v17
	s_nop 0
	v_add_u32_e32 v21, -1, v20
	v_fma_f32 v22, -v21, v20, v17
	v_cmp_ge_f32_e64 s[0:1], 0, v22
	v_add_u32_e32 v22, 1, v20
	s_nop 0
	v_cndmask_b32_e64 v21, v20, v21, s[0:1]
	v_fma_f32 v20, -v22, v20, v17
	v_cmp_lt_f32_e64 s[0:1], 0, v20
	s_nop 1
	v_cndmask_b32_e64 v20, v21, v22, s[0:1]
	v_mul_f32_e32 v21, 0x37800000, v20
	v_cndmask_b32_e32 v20, v20, v21, vcc
	v_cmp_class_f32_e32 vcc, v17, v180
	s_nop 1
	v_cndmask_b32_e32 v17, v20, v17, vcc
	v_div_scale_f32 v20, s[0:1], v17, v17, 1.0
	v_rcp_f32_e32 v21, v20
	s_nop 0
	v_fma_f32 v22, -v20, v21, 1.0
	v_fmac_f32_e32 v21, v22, v21
	v_div_scale_f32 v22, vcc, 1.0, v17, 1.0
	v_mul_f32_e32 v23, v22, v21
	v_fma_f32 v24, -v20, v23, v22
	v_fmac_f32_e32 v23, v24, v21
	v_fma_f32 v20, -v20, v23, v22
	v_div_fmas_f32 v20, v20, v21, v23
	v_div_fixup_f32 v17, v20, v17, 1.0
	v_mul_f32_e32 v18, v18, v17
	v_mul_f32_e32 v18, v34, v18
	v_bfe_u32 v20, v18, 16, 1
	v_add3_u32 v18, v18, v20, s70
	global_store_short_d16_hi v[14:15], v18, off
	v_mul_f32_e32 v18, v19, v17
	v_mul_f32_e32 v18, v35, v18
	v_bfe_u32 v19, v18, 16, 1
	v_mul_f32_e32 v9, v9, v17
	v_add3_u32 v18, v18, v19, s70
	v_mul_f32_e32 v9, v36, v9
	global_store_short_d16_hi v[14:15], v18, off offset:64
	v_bfe_u32 v18, v9, 16, 1
	v_add3_u32 v9, v9, v18, s70
	global_store_short_d16_hi v[14:15], v9, off offset:128
	v_mul_f32_e32 v9, v16, v17
	v_mul_f32_e32 v9, v37, v9
	v_bfe_u32 v16, v9, 16, 1
	v_add3_u32 v9, v9, v16, s70
	global_store_short_d16_hi v[14:15], v9, off offset:192
	v_add_u32_e32 v9, v12, v8
	v_lshl_add_u32 v9, v9, 7, v124
	v_lshl_add_u32 v9, v9, 2, 0
	v_lshlrev_b64 v[12:13], 12, v[12:13]
	v_lshl_add_u64 v[12:13], v[4:5], 0, v[12:13]
	s_waitcnt lgkmcnt(1)
	v_fma_f32 v16, -v160, v236, v72
	v_fma_f32 v17, -v160, v237, v73
	v_mul_f32_e32 v18, v17, v17
	v_fmac_f32_e32 v18, v16, v16
	s_waitcnt lgkmcnt(0)
	v_add_u32_e32 v244, v10, v8
	v_lshl_add_u32 v244, v244, 7, v124
	v_lshl_add_u32 v244, v244, 2, 0
	ds_read2_b32 v[240:241], v244 offset1:32
	ds_read2_b32 v[242:243], v244 offset0:64 offset1:96
	v_fma_f32 v9, -v160, v238, v42
	v_fmac_f32_e32 v18, v9, v9
	v_fma_f32 v14, -v160, v239, v43
	v_fmac_f32_e32 v18, v14, v14
	s_nop 1
	v_mov_b32_dpp v15, v18 quad_perm:[1,0,3,2] row_mask:0xf bank_mask:0xf
	v_add_f32_e32 v15, v18, v15
	s_nop 1
	v_mov_b32_dpp v18, v15 quad_perm:[2,3,0,1] row_mask:0xf bank_mask:0xf
	v_add_f32_e32 v15, v15, v18
	s_nop 1
	v_mov_b32_dpp v18, v15 row_half_mirror row_mask:0xf bank_mask:0xf
	s_nop 1
	v_mov_b32_dpp v18, v18 quad_perm:[3,2,1,0] row_mask:0xf bank_mask:0xf
	v_add_f32_e32 v15, v15, v18
	s_nop 1
	v_mov_b32_dpp v18, v15 row_ror:8 row_mask:0xf bank_mask:0xf
	v_add_f32_e32 v15, v15, v18
	v_mov_b32_e32 v18, v15
	s_nop 1
	v_permlane16_swap_b32_e32 v15, v18
	v_add_f32_e32 v15, v15, v18
	v_fmamk_f32 v15, v15, 0x3c000000, v179
	v_cmp_gt_f32_e32 vcc, s4, v15
	v_mul_f32_e32 v18, 0x4f800000, v15
	s_nop 0
	v_cndmask_b32_e32 v15, v15, v18, vcc
	v_sqrt_f32_e32 v18, v15
	s_nop 0
	v_add_u32_e32 v19, -1, v18
	v_fma_f32 v20, -v19, v18, v15
	v_cmp_ge_f32_e64 s[0:1], 0, v20
	v_add_u32_e32 v20, 1, v18
	s_nop 0
	v_cndmask_b32_e64 v19, v18, v19, s[0:1]
	v_fma_f32 v18, -v20, v18, v15
	v_cmp_lt_f32_e64 s[0:1], 0, v18
	s_nop 1
	v_cndmask_b32_e64 v18, v19, v20, s[0:1]
	v_mul_f32_e32 v19, 0x37800000, v18
	v_cndmask_b32_e32 v18, v18, v19, vcc
	v_cmp_class_f32_e32 vcc, v15, v180
	s_nop 1
	v_cndmask_b32_e32 v15, v18, v15, vcc
	v_div_scale_f32 v18, s[0:1], v15, v15, 1.0
	v_rcp_f32_e32 v19, v18
	s_nop 0
	v_fma_f32 v20, -v18, v19, 1.0
	v_fmac_f32_e32 v19, v20, v19
	v_div_scale_f32 v20, vcc, 1.0, v15, 1.0
	v_mul_f32_e32 v21, v20, v19
	v_fma_f32 v22, -v18, v21, v20
	v_fmac_f32_e32 v21, v22, v19
	v_fma_f32 v18, -v18, v21, v20
	v_div_fmas_f32 v18, v18, v19, v21
	v_div_fixup_f32 v15, v18, v15, 1.0
	v_mul_f32_e32 v16, v16, v15
	v_mul_f32_e32 v16, v34, v16
	v_bfe_u32 v18, v16, 16, 1
	v_add3_u32 v16, v16, v18, s70
	global_store_short_d16_hi v[12:13], v16, off
	v_mul_f32_e32 v16, v17, v15
	v_mul_f32_e32 v16, v35, v16
	v_bfe_u32 v17, v16, 16, 1
	v_mul_f32_e32 v9, v9, v15
	v_add3_u32 v16, v16, v17, s70
	v_mul_f32_e32 v9, v36, v9
	global_store_short_d16_hi v[12:13], v16, off offset:64
	v_bfe_u32 v16, v9, 16, 1
	v_add3_u32 v9, v9, v16, s70
	global_store_short_d16_hi v[12:13], v9, off offset:128
	v_mul_f32_e32 v9, v14, v15
	v_mul_f32_e32 v9, v37, v9
	v_bfe_u32 v14, v9, 16, 1
	v_add3_u32 v9, v9, v14, s70
	global_store_short_d16_hi v[12:13], v9, off offset:192
	v_add_u32_e32 v9, v10, v8
	v_lshl_add_u32 v9, v9, 7, v124
	v_lshl_add_u32 v9, v9, 2, 0
	v_lshlrev_b64 v[10:11], 12, v[10:11]
	v_lshl_add_u64 v[10:11], v[4:5], 0, v[10:11]
	s_waitcnt lgkmcnt(1)
; __device__ __forceinline__ unsigned f2bf(float f) { unsigned u = __builtin_bit_cast(unsigned, f); return (u + 0x7fffu + ((u >> 16) & 1u)) >> 16; }
; __device__ __forceinline__ int crow(int r, int hi) { return (r & 3) + 8 * (r >> 2) + 4 * hi; }
; __device__ __forceinline__ void attn_unit(const bf16* __restrict__ Qb, const bf16* __restrict__ Kh, const bf16* __restrict__ Vh, int klat0, int nlt, int kctx0, int NT,
;                                           float lam, float post, const float* __restrict__ subw, bf16* __restrict__ Ob, char* lds) {
;     ...
;     for (int r = 0; r < 16; ++r) { const int orow = crow(r, hi_e); float v[4]; float ss = 0.f;
; #pragma unroll
;       for (int d0 = 0; d0 < 4; ++d0) { v[d0] = o[d0][r] - lam * X[(wq_e * 32 + orow) * 128 + d0 * 32 + r32_e]; ss += v[d0] * v[d0]; }
;       ss += __shfl_xor(ss, 1); ss += __shfl_xor(ss, 2); ss += __shfl_xor(ss, 4); ss += __shfl_xor(ss, 8); ss += __shfl_xor(ss, 16);
;       const float rs = 1.0f / sqrtf(ss * (1.0f / 128.0f) + LN_EPS);
; #pragma unroll
;       for (int d0 = 0; d0 < 4; ++d0) Ow[(long)orow * DM + d0 * 32 + r32_e] = (bf16)f2bf(v[d0] * rs * sw[d0]); }
	v_fma_f32 v14, -v160, v240, v70
	v_fma_f32 v15, -v160, v241, v71
	v_mul_f32_e32 v16, v15, v15
	v_fmac_f32_e32 v16, v14, v14
	s_waitcnt lgkmcnt(0)
	v_add_u32_e32 v244, v6, v8
	v_lshl_add_u32 v244, v244, 7, v124
	v_lshl_add_u32 v244, v244, 2, 0
	ds_read2_b32 v[236:237], v244 offset1:32
	ds_read2_b32 v[238:239], v244 offset0:64 offset1:96
	v_fma_f32 v9, -v160, v242, v40
	v_fmac_f32_e32 v16, v9, v9
	v_fma_f32 v12, -v160, v243, v41
	v_fmac_f32_e32 v16, v12, v12
	s_nop 1
	v_mov_b32_dpp v13, v16 quad_perm:[1,0,3,2] row_mask:0xf bank_mask:0xf
	v_add_f32_e32 v13, v16, v13
	s_nop 1
	v_mov_b32_dpp v16, v13 quad_perm:[2,3,0,1] row_mask:0xf bank_mask:0xf
	v_add_f32_e32 v13, v13, v16
	s_nop 1
	v_mov_b32_dpp v16, v13 row_half_mirror row_mask:0xf bank_mask:0xf
	s_nop 1
	v_mov_b32_dpp v16, v16 quad_perm:[3,2,1,0] row_mask:0xf bank_mask:0xf
	v_add_f32_e32 v13, v13, v16
	s_nop 1
	v_mov_b32_dpp v16, v13 row_ror:8 row_mask:0xf bank_mask:0xf
	v_add_f32_e32 v13, v13, v16
	v_mov_b32_e32 v16, v13
	s_nop 1
	v_permlane16_swap_b32_e32 v13, v16
	v_add_f32_e32 v13, v13, v16
	v_fmamk_f32 v13, v13, 0x3c000000, v179
	v_cmp_gt_f32_e32 vcc, s4, v13
	v_mul_f32_e32 v16, 0x4f800000, v13
	s_nop 0
	v_cndmask_b32_e32 v13, v13, v16, vcc
	v_sqrt_f32_e32 v16, v13
	s_nop 0
	v_add_u32_e32 v17, -1, v16
	v_fma_f32 v18, -v17, v16, v13
	v_cmp_ge_f32_e64 s[0:1], 0, v18
	v_add_u32_e32 v18, 1, v16
	s_nop 0
	v_cndmask_b32_e64 v17, v16, v17, s[0:1]
	v_fma_f32 v16, -v18, v16, v13
	v_cmp_lt_f32_e64 s[0:1], 0, v16
	s_nop 1
	v_cndmask_b32_e64 v16, v17, v18, s[0:1]
	v_mul_f32_e32 v17, 0x37800000, v16
	v_cndmask_b32_e32 v16, v16, v17, vcc
	v_cmp_class_f32_e32 vcc, v13, v180
	s_nop 1
	v_cndmask_b32_e32 v13, v16, v13, vcc
	v_div_scale_f32 v16, s[0:1], v13, v13, 1.0
	v_rcp_f32_e32 v17, v16
	s_nop 0
	v_fma_f32 v18, -v16, v17, 1.0
	v_fmac_f32_e32 v17, v18, v17
	v_div_scale_f32 v18, vcc, 1.0, v13, 1.0
	v_mul_f32_e32 v19, v18, v17
	v_fma_f32 v20, -v16, v19, v18
	v_fmac_f32_e32 v19, v20, v17
	v_fma_f32 v16, -v16, v19, v18
	v_div_fmas_f32 v16, v16, v17, v19
	v_div_fixup_f32 v13, v16, v13, 1.0
	v_mul_f32_e32 v14, v14, v13
	v_mul_f32_e32 v14, v34, v14
	v_bfe_u32 v16, v14, 16, 1
	v_add3_u32 v14, v14, v16, s70
	global_store_short_d16_hi v[10:11], v14, off
	v_mul_f32_e32 v14, v15, v13
	v_mul_f32_e32 v14, v35, v14
	v_bfe_u32 v15, v14, 16, 1
	v_mul_f32_e32 v9, v9, v13
	v_add3_u32 v14, v14, v15, s70
	v_mul_f32_e32 v9, v36, v9
	global_store_short_d16_hi v[10:11], v14, off offset:64
	v_bfe_u32 v14, v9, 16, 1
	v_add3_u32 v9, v9, v14, s70
	global_store_short_d16_hi v[10:11], v9, off offset:128
	v_mul_f32_e32 v9, v12, v13
	v_mul_f32_e32 v9, v37, v9
	v_bfe_u32 v12, v9, 16, 1
	v_add3_u32 v9, v9, v12, s70
	global_store_short_d16_hi v[10:11], v9, off offset:192
	v_add_u32_e32 v9, v6, v8
	v_lshl_add_u32 v9, v9, 7, v124
	v_lshl_add_u32 v9, v9, 2, 0
	v_lshlrev_b64 v[6:7], 12, v[6:7]
	v_lshl_add_u64 v[6:7], v[4:5], 0, v[6:7]
	s_waitcnt lgkmcnt(1)
	v_fma_f32 v12, -v160, v236, v68
	v_fma_f32 v13, -v160, v237, v69
	v_mul_f32_e32 v14, v13, v13
	v_fmac_f32_e32 v14, v12, v12
	s_waitcnt lgkmcnt(0)
; __device__ __forceinline__ unsigned f2bf(float f) { unsigned u = __builtin_bit_cast(unsigned, f); return (u + 0x7fffu + ((u >> 16) & 1u)) >> 16; }
; __device__ __forceinline__ int crow(int r, int hi) { return (r & 3) + 8 * (r >> 2) + 4 * hi; }
; __device__ __forceinline__ void attn_unit(const bf16* __restrict__ Qb, const bf16* __restrict__ Kh, const bf16* __restrict__ Vh, int klat0, int nlt, int kctx0, int NT,
;                                           float lam, float post, const float* __restrict__ subw, bf16* __restrict__ Ob, char* lds) {
;     ...
;     for (int r = 0; r < 16; ++r) { const int orow = crow(r, hi_e); float v[4]; float ss = 0.f;
; #pragma unroll
;       for (int d0 = 0; d0 < 4; ++d0) { v[d0] = o[d0][r] - lam * X[(wq_e * 32 + orow) * 128 + d0 * 32 + r32_e]; ss += v[d0] * v[d0]; }
;       ss += __shfl_xor(ss, 1); ss += __shfl_xor(ss, 2); ss += __shfl_xor(ss, 4); ss += __shfl_xor(ss, 8); ss += __shfl_xor(ss, 16);
;       const float rs = 1.0f / sqrtf(ss * (1.0f / 128.0f) + LN_EPS);
; #pragma unroll
;       for (int d0 = 0; d0 < 4; ++d0) Ow[(long)orow * DM + d0 * 32 + r32_e] = (bf16)f2bf(v[d0] * rs * sw[d0]); }
	v_add_u32_e32 v245, v2, v8
	v_lshl_add_u32 v245, v245, 7, v124
	v_lshl_add_u32 v244, v245, 2, 0
	ds_read2_b32 v[240:241], v244 offset1:32
	ds_read2_b32 v[242:243], v244 offset0:64 offset1:96
	v_fma_f32 v9, -v160, v238, v38
	v_fmac_f32_e32 v14, v9, v9
	v_fma_f32 v10, -v160, v239, v39
	v_fmac_f32_e32 v14, v10, v10
	s_nop 1
	v_mov_b32_dpp v11, v14 quad_perm:[1,0,3,2] row_mask:0xf bank_mask:0xf
	v_add_f32_e32 v11, v14, v11
	s_nop 1
	v_mov_b32_dpp v14, v11 quad_perm:[2,3,0,1] row_mask:0xf bank_mask:0xf
	v_add_f32_e32 v11, v11, v14
	s_nop 1
	v_mov_b32_dpp v14, v11 row_half_mirror row_mask:0xf bank_mask:0xf
	s_nop 1
	v_mov_b32_dpp v14, v14 quad_perm:[3,2,1,0] row_mask:0xf bank_mask:0xf
	v_add_f32_e32 v11, v11, v14
	s_nop 1
	v_mov_b32_dpp v14, v11 row_ror:8 row_mask:0xf bank_mask:0xf
	v_add_f32_e32 v11, v11, v14
	v_mov_b32_e32 v14, v11
	s_nop 1
	v_permlane16_swap_b32_e32 v11, v14
	v_add_f32_e32 v11, v11, v14
	v_fmamk_f32 v11, v11, 0x3c000000, v179
	v_cmp_gt_f32_e32 vcc, s4, v11
	v_mul_f32_e32 v14, 0x4f800000, v11
	s_nop 0
	v_cndmask_b32_e32 v11, v11, v14, vcc
	v_sqrt_f32_e32 v14, v11
	s_nop 0
	v_add_u32_e32 v15, -1, v14
	v_fma_f32 v16, -v15, v14, v11
	v_cmp_ge_f32_e64 s[0:1], 0, v16
	v_add_u32_e32 v16, 1, v14
	s_nop 0
	v_cndmask_b32_e64 v15, v14, v15, s[0:1]
	v_fma_f32 v14, -v16, v14, v11
	v_cmp_lt_f32_e64 s[0:1], 0, v14
	s_nop 1
	v_cndmask_b32_e64 v14, v15, v16, s[0:1]
	v_mul_f32_e32 v15, 0x37800000, v14
	v_cndmask_b32_e32 v14, v14, v15, vcc
	v_cmp_class_f32_e32 vcc, v11, v180
	s_nop 1
	v_cndmask_b32_e32 v11, v14, v11, vcc
	v_div_scale_f32 v14, s[0:1], v11, v11, 1.0
	v_rcp_f32_e32 v15, v14
	s_nop 0
	v_fma_f32 v16, -v14, v15, 1.0
	v_fmac_f32_e32 v15, v16, v15
	v_div_scale_f32 v16, vcc, 1.0, v11, 1.0
	v_mul_f32_e32 v17, v16, v15
	v_fma_f32 v18, -v14, v17, v16
	v_fmac_f32_e32 v17, v18, v15
	v_fma_f32 v14, -v14, v17, v16
	v_div_fmas_f32 v14, v14, v15, v17
	v_div_fixup_f32 v11, v14, v11, 1.0
	v_mul_f32_e32 v12, v12, v11
	v_mul_f32_e32 v12, v34, v12
	v_bfe_u32 v14, v12, 16, 1
	v_add3_u32 v12, v12, v14, s70
	global_store_short_d16_hi v[6:7], v12, off
	v_mul_f32_e32 v12, v13, v11
	v_mul_f32_e32 v12, v35, v12
	v_bfe_u32 v13, v12, 16, 1
	v_mul_f32_e32 v9, v9, v11
	v_add3_u32 v12, v12, v13, s70
	v_mul_f32_e32 v9, v36, v9
	global_store_short_d16_hi v[6:7], v12, off offset:64
	v_bfe_u32 v12, v9, 16, 1
	v_add3_u32 v9, v9, v12, s70
	global_store_short_d16_hi v[6:7], v9, off offset:128
	v_mul_f32_e32 v9, v10, v11
	v_mul_f32_e32 v9, v37, v9
	v_bfe_u32 v10, v9, 16, 1
	v_add3_u32 v9, v9, v10, s70
	global_store_short_d16_hi v[6:7], v9, off offset:192
	v_add_u32_e32 v6, v2, v8
	v_lshl_add_u32 v6, v6, 7, v124
	v_lshl_add_u32 v8, v6, 2, 0
	v_lshlrev_b64 v[2:3], 12, v[2:3]
	v_lshl_add_u64 v[2:3], v[4:5], 0, v[2:3]
	s_waitcnt lgkmcnt(1)
	v_fma_f32 v9, -v160, v240, v66
	v_fma_f32 v10, -v160, v241, v67
	v_mul_f32_e32 v11, v10, v10
	v_fmac_f32_e32 v11, v9, v9
	s_waitcnt lgkmcnt(0)
	v_fma_f32 v6, -v160, v242, v32
	v_fmac_f32_e32 v11, v6, v6
	v_fma_f32 v7, -v160, v243, v33
	v_fmac_f32_e32 v11, v7, v7
	s_nop 1
	v_mov_b32_dpp v8, v11 quad_perm:[1,0,3,2] row_mask:0xf bank_mask:0xf
	s_waitcnt lgkmcnt(0)
	v_add_f32_e32 v8, v11, v8
	s_nop 1
	v_mov_b32_dpp v11, v8 quad_perm:[2,3,0,1] row_mask:0xf bank_mask:0xf
	s_waitcnt lgkmcnt(0)
	v_add_f32_e32 v8, v8, v11
	s_nop 1
	v_mov_b32_dpp v11, v8 row_half_mirror row_mask:0xf bank_mask:0xf
	s_nop 1
	v_mov_b32_dpp v11, v11 quad_perm:[3,2,1,0] row_mask:0xf bank_mask:0xf
	s_waitcnt lgkmcnt(0)
	v_add_f32_e32 v8, v8, v11
	s_nop 1
	v_mov_b32_dpp v11, v8 row_ror:8 row_mask:0xf bank_mask:0xf
	s_waitcnt lgkmcnt(0)
	v_add_f32_e32 v8, v8, v11
	v_mov_b32_e32 v11, v8
	s_nop 1
	v_permlane16_swap_b32_e32 v8, v11
	s_waitcnt lgkmcnt(0)
	v_add_f32_e32 v8, v8, v11
	v_fmamk_f32 v8, v8, 0x3c000000, v179
	v_cmp_gt_f32_e32 vcc, s4, v8
	v_mul_f32_e32 v11, 0x4f800000, v8
	s_nop 0
	v_cndmask_b32_e32 v8, v8, v11, vcc
	v_sqrt_f32_e32 v11, v8
	s_nop 0
	v_add_u32_e32 v12, -1, v11
	v_fma_f32 v13, -v12, v11, v8
	v_cmp_ge_f32_e64 s[0:1], 0, v13
	v_add_u32_e32 v13, 1, v11
	s_nop 0
	v_cndmask_b32_e64 v12, v11, v12, s[0:1]
	v_fma_f32 v11, -v13, v11, v8
	v_cmp_lt_f32_e64 s[0:1], 0, v11
	s_nop 1
	v_cndmask_b32_e64 v11, v12, v13, s[0:1]
	v_mul_f32_e32 v12, 0x37800000, v11
	v_cndmask_b32_e32 v11, v11, v12, vcc
	v_cmp_class_f32_e32 vcc, v8, v180
	s_nop 1
	v_cndmask_b32_e32 v8, v11, v8, vcc
	v_div_scale_f32 v11, s[0:1], v8, v8, 1.0
	v_rcp_f32_e32 v12, v11
	s_nop 0
	v_fma_f32 v13, -v11, v12, 1.0
	v_fmac_f32_e32 v12, v13, v12
	v_div_scale_f32 v13, vcc, 1.0, v8, 1.0
	v_mul_f32_e32 v14, v13, v12
	v_fma_f32 v15, -v11, v14, v13
	v_fmac_f32_e32 v14, v15, v12
	v_fma_f32 v11, -v11, v14, v13
	v_div_fmas_f32 v11, v11, v12, v14
	v_div_fixup_f32 v8, v11, v8, 1.0
	v_mul_f32_e32 v4, v9, v8
	v_mul_f32_e32 v4, v34, v4
	v_bfe_u32 v5, v4, 16, 1
	v_add3_u32 v4, v4, v5, s70
	global_store_short_d16_hi v[2:3], v4, off
	v_mul_f32_e32 v4, v10, v8
	v_mul_f32_e32 v4, v35, v4
	v_bfe_u32 v5, v4, 16, 1
	v_add3_u32 v4, v4, v5, s70
	global_store_short_d16_hi v[2:3], v4, off offset:64
	v_mul_f32_e32 v4, v6, v8
	v_mul_f32_e32 v4, v36, v4
	v_bfe_u32 v5, v4, 16, 1
	v_add3_u32 v4, v4, v5, s70
	global_store_short_d16_hi v[2:3], v4, off offset:128
	v_mul_f32_e32 v4, v7, v8
	v_mul_f32_e32 v4, v37, v4
	v_bfe_u32 v5, v4, 16, 1
	v_add3_u32 v4, v4, v5, s70
	global_store_short_d16_hi v[2:3], v4, off offset:192
